# PEER top-k: product-key combination stage (top 16 of 50 sums, softmax weights, index lookups) rewritten as a selection network with batched LDS reads
# speedup vs baseline: 1.0187x; 1.0101x over previous
; __device__ __forceinline__ void peer_topk_item(PREF P, int w, char* smem) {
;     ...
;   if (tid < 64) {
;     const int t = tid;
;     float a[16], b[16];
; #pragma unroll
;     for (int k = 0; k < 16; ++k) {
;       a[k] = __uint_as_float(__float_as_uint(Ll[t * 17 + k]) & ~127u);
;       b[k] = __uint_as_float(__float_as_uint(Ll[(64 + t) * 17 + k]) & ~127u);
;     }
;     float top[16];
; #pragma unroll
;     for (int k = 0; k < 16; ++k) top[k] = -3.0e38f;
; #pragma unroll
;     for (int i = 0; i < 16; ++i)
; #pragma unroll
;       for (int j = 0; j < 16; ++j)
;         if ((i + 1) * (j + 1) <= 16) {
;           float s = a[i] + b[j];
;           s = __uint_as_float((__float_as_uint(s) & ~255u) | (unsigned)(i * 16 + j));
;           ce_insert(top, s);
;         }
.LBB0_635:
	s_or_b64 exec, exec, s[4:5]
	v_cmp_gt_i32_e32 vcc, 64, v53
	s_waitcnt lgkmcnt(0)
	s_barrier
	s_and_saveexec_b64 s[4:5], vcc
	s_cbranch_execz .LBB0_626
	s_movk_i32 s6, 0x44
	v_mul_lo_u32 v0, v53, s6
	v_add_u32_e32 v4, 0x10200, v0
	v_add_u32_e32 v5, 0x1100, v4
	ds_read2_b32 v[6:7], v4 offset0:0 offset1:1
	ds_read2_b32 v[8:9], v4 offset0:2 offset1:3
	ds_read2_b32 v[10:11], v4 offset0:4 offset1:5
	ds_read2_b32 v[12:13], v4 offset0:6 offset1:7
	ds_read2_b32 v[14:15], v4 offset0:8 offset1:9
	ds_read2_b32 v[16:17], v4 offset0:10 offset1:11
	ds_read2_b32 v[18:19], v4 offset0:12 offset1:13
	ds_read2_b32 v[20:21], v4 offset0:14 offset1:15
	ds_read2_b32 v[22:23], v5 offset0:0 offset1:1
	ds_read2_b32 v[24:25], v5 offset0:2 offset1:3
	ds_read2_b32 v[26:27], v5 offset0:4 offset1:5
	ds_read2_b32 v[28:29], v5 offset0:6 offset1:7
	ds_read2_b32 v[30:31], v5 offset0:8 offset1:9
	ds_read2_b32 v[32:33], v5 offset0:10 offset1:11
	ds_read2_b32 v[34:35], v5 offset0:12 offset1:13
	ds_read2_b32 v[36:37], v5 offset0:14 offset1:15
	ds_read2_b64 v[0:3], v52 offset0:48 offset1:65
	s_waitcnt lgkmcnt(9)
	v_and_b32_e32 v6, 0xffffff80, v6
	v_and_b32_e32 v7, 0xffffff80, v7
	v_and_b32_e32 v8, 0xffffff80, v8
	v_and_b32_e32 v9, 0xffffff80, v9
	v_and_b32_e32 v10, 0xffffff80, v10
	v_and_b32_e32 v11, 0xffffff80, v11
	v_and_b32_e32 v12, 0xffffff80, v12
	v_and_b32_e32 v13, 0xffffff80, v13
	v_and_b32_e32 v14, 0xffffff80, v14
	v_and_b32_e32 v15, 0xffffff80, v15
	v_and_b32_e32 v16, 0xffffff80, v16
	v_and_b32_e32 v17, 0xffffff80, v17
	v_and_b32_e32 v18, 0xffffff80, v18
	v_and_b32_e32 v19, 0xffffff80, v19
	v_and_b32_e32 v20, 0xffffff80, v20
	v_and_b32_e32 v21, 0xffffff80, v21
	s_waitcnt lgkmcnt(1)
	v_and_b32_e32 v22, 0xffffff80, v22
	v_and_b32_e32 v23, 0xffffff80, v23
	v_and_b32_e32 v24, 0xffffff80, v24
	v_and_b32_e32 v25, 0xffffff80, v25
	v_and_b32_e32 v26, 0xffffff80, v26
	v_and_b32_e32 v27, 0xffffff80, v27
	v_and_b32_e32 v28, 0xffffff80, v28
	v_and_b32_e32 v29, 0xffffff80, v29
	v_and_b32_e32 v30, 0xffffff80, v30
	v_and_b32_e32 v31, 0xffffff80, v31
	v_and_b32_e32 v32, 0xffffff80, v32
	v_and_b32_e32 v33, 0xffffff80, v33
	v_and_b32_e32 v34, 0xffffff80, v34
	v_and_b32_e32 v35, 0xffffff80, v35
	v_and_b32_e32 v36, 0xffffff80, v36
	v_and_b32_e32 v37, 0xffffff80, v37
	v_add_f32_e32 v66, v6, v22
	v_add_f32_e32 v67, v6, v23
	v_add_f32_e32 v68, v6, v24
	v_add_f32_e32 v69, v6, v25
	v_add_f32_e32 v70, v6, v26
	v_add_f32_e32 v71, v6, v27
	v_add_f32_e32 v72, v6, v28
	v_add_f32_e32 v73, v6, v29
	v_add_f32_e32 v74, v6, v30
	v_add_f32_e32 v75, v6, v31
	v_add_f32_e32 v76, v6, v32
	v_add_f32_e32 v77, v6, v33
	v_add_f32_e32 v78, v6, v34
	v_add_f32_e32 v79, v6, v35
	v_add_f32_e32 v80, v6, v36
	v_add_f32_e32 v81, v6, v37
	v_add_f32_e32 v82, v7, v22
	v_add_f32_e32 v83, v7, v23
	v_add_f32_e32 v84, v7, v24
	v_add_f32_e32 v85, v7, v25
	v_add_f32_e32 v86, v7, v26
	v_add_f32_e32 v87, v7, v27
	v_add_f32_e32 v88, v7, v28
	v_add_f32_e32 v89, v7, v29
	v_add_f32_e32 v90, v8, v22
	v_add_f32_e32 v91, v8, v23
	v_add_f32_e32 v92, v8, v24
	v_add_f32_e32 v93, v8, v25
	v_add_f32_e32 v94, v8, v26
	v_add_f32_e32 v95, v9, v22
	v_add_f32_e32 v96, v9, v23
	v_add_f32_e32 v97, v9, v24
	v_add_f32_e32 v98, v9, v25
	v_add_f32_e32 v99, v10, v22
	v_add_f32_e32 v100, v10, v23
	v_add_f32_e32 v101, v10, v24
	v_add_f32_e32 v102, v11, v22
	v_add_f32_e32 v103, v11, v23
	v_add_f32_e32 v104, v12, v22
	v_add_f32_e32 v105, v12, v23
	v_add_f32_e32 v106, v13, v22
	v_add_f32_e32 v107, v13, v23
	v_add_f32_e32 v108, v14, v22
	v_add_f32_e32 v109, v15, v22
	v_add_f32_e32 v110, v16, v22
	v_add_f32_e32 v111, v17, v22
	v_add_f32_e32 v112, v18, v22
	v_add_f32_e32 v113, v19, v22
	v_add_f32_e32 v114, v20, v22
	v_add_f32_e32 v115, v21, v22
	v_and_b32_e32 v66, 0xffffff00, v66
	v_and_or_b32 v67, v67, s13, 1
	v_and_or_b32 v68, v68, s13, 2
	v_and_or_b32 v69, v69, s13, 3
	v_and_or_b32 v70, v70, s13, 4
	v_and_or_b32 v71, v71, s13, 5
	v_and_or_b32 v72, v72, s13, 6
	v_and_or_b32 v73, v73, s13, 7
	v_and_or_b32 v74, v74, s13, 8
	v_and_or_b32 v75, v75, s13, 9
	v_and_or_b32 v76, v76, s13, 10
	v_and_or_b32 v77, v77, s13, 11
	v_and_or_b32 v78, v78, s13, 12
	v_and_or_b32 v79, v79, s13, 13
	v_and_or_b32 v80, v80, s13, 14
	v_and_or_b32 v81, v81, s13, 15
	v_and_or_b32 v82, v82, s13, 16
	v_and_or_b32 v83, v83, s13, 17
	v_and_or_b32 v84, v84, s13, 18
	v_and_or_b32 v85, v85, s13, 19
	v_and_or_b32 v86, v86, s13, 20
	v_and_or_b32 v87, v87, s13, 21
	v_and_or_b32 v88, v88, s13, 22
	v_and_or_b32 v89, v89, s13, 23
	v_and_or_b32 v90, v90, s13, 32
	v_and_or_b32 v91, v91, s13, 33
	v_and_or_b32 v92, v92, s13, 34
	v_and_or_b32 v93, v93, s13, 35
	v_and_or_b32 v94, v94, s13, 36
	v_and_or_b32 v95, v95, s13, 48
	v_and_or_b32 v96, v96, s13, 49
	v_and_or_b32 v97, v97, s13, 50
	v_and_or_b32 v98, v98, s13, 51
	v_and_or_b32 v99, v99, s13, 64
	v_and_b32_e32 v100, s13, v100
	v_or_b32_e32 v100, 0x41, v100
	v_and_b32_e32 v101, s13, v101
	v_or_b32_e32 v101, 0x42, v101
	v_and_b32_e32 v102, s13, v102
	v_or_b32_e32 v102, 0x50, v102
	v_and_b32_e32 v103, s13, v103
	v_or_b32_e32 v103, 0x51, v103
	v_and_b32_e32 v104, s13, v104
	v_or_b32_e32 v104, 0x60, v104
	v_and_b32_e32 v105, s13, v105
	v_or_b32_e32 v105, 0x61, v105
	v_and_b32_e32 v106, s13, v106
	v_or_b32_e32 v106, 0x70, v106
	v_and_b32_e32 v107, s13, v107
	v_or_b32_e32 v107, 0x71, v107
	v_and_b32_e32 v108, s13, v108
	v_or_b32_e32 v108, 0x80, v108
	v_and_b32_e32 v109, s13, v109
	v_or_b32_e32 v109, 0x90, v109
	v_and_b32_e32 v110, s13, v110
	v_or_b32_e32 v110, 0xa0, v110
	v_and_b32_e32 v111, s13, v111
	v_or_b32_e32 v111, 0xb0, v111
	v_and_b32_e32 v112, s13, v112
	v_or_b32_e32 v112, 0xc0, v112
	v_and_b32_e32 v113, s13, v113
	v_or_b32_e32 v113, 0xd0, v113
; __device__ __forceinline__ void peer_topk_item(PREF P, int w, char* smem) {
;     ...
; #pragma unroll
;     for (int i = 0; i < 16; ++i)
; #pragma unroll
;       for (int j = 0; j < 16; ++j)
;         if ((i + 1) * (j + 1) <= 16) {
;           float s = a[i] + b[j];
;           s = __uint_as_float((__float_as_uint(s) & ~255u) | (unsigned)(i * 16 + j));
;           ce_insert(top, s);
;         }
	v_and_b32_e32 v114, s13, v114
	v_or_b32_e32 v114, 0xe0, v114
	v_and_b32_e32 v115, s13, v115
	v_or_b32_e32 v115, 0xf0, v115
	v_max_f32_e32 v116, v66, v67
	v_min_f32_e32 v117, v66, v67
	v_max_f32_e32 v118, v68, v69
	v_min_f32_e32 v119, v68, v69
	v_max_f32_e32 v120, v116, v118
	v_min_f32_e32 v121, v116, v118
	v_max_f32_e32 v122, v117, v119
	v_min_f32_e32 v123, v117, v119
	v_max_f32_e32 v124, v122, v121
	v_min_f32_e32 v125, v122, v121
	v_max_f32_e32 v126, v70, v71
	v_min_f32_e32 v127, v70, v71
	v_max_f32_e32 v128, v72, v73
	v_min_f32_e32 v129, v72, v73
	v_max_f32_e32 v130, v126, v128
	v_min_f32_e32 v131, v126, v128
	v_max_f32_e32 v132, v127, v129
	v_min_f32_e32 v133, v127, v129
	v_max_f32_e32 v134, v132, v131
	v_min_f32_e32 v135, v132, v131
	v_max_f32_e32 v136, v120, v130
	v_min_f32_e32 v137, v120, v130
	v_max_f32_e32 v138, v125, v135
	v_min_f32_e32 v139, v125, v135
	v_max_f32_e32 v140, v138, v137
	v_min_f32_e32 v141, v138, v137
	v_max_f32_e32 v142, v124, v134
	v_min_f32_e32 v143, v124, v134
	v_max_f32_e32 v144, v123, v133
	v_min_f32_e32 v145, v123, v133
	v_max_f32_e32 v146, v144, v143
	v_min_f32_e32 v147, v144, v143
	v_max_f32_e32 v148, v142, v140
	v_min_f32_e32 v149, v142, v140
	v_max_f32_e32 v150, v146, v141
	v_min_f32_e32 v151, v146, v141
	v_max_f32_e32 v152, v147, v139
	v_min_f32_e32 v153, v147, v139
	v_max_f32_e32 v154, v74, v75
	v_min_f32_e32 v155, v74, v75
	v_max_f32_e32 v156, v76, v77
	v_min_f32_e32 v157, v76, v77
	v_max_f32_e32 v158, v154, v156
	v_min_f32_e32 v159, v154, v156
	v_max_f32_e32 v160, v155, v157
	v_min_f32_e32 v161, v155, v157
	v_max_f32_e32 v162, v160, v159
	v_min_f32_e32 v163, v160, v159
	v_max_f32_e32 v164, v78, v79
	v_min_f32_e32 v165, v78, v79
	v_max_f32_e32 v166, v80, v81
	v_min_f32_e32 v167, v80, v81
	v_max_f32_e32 v168, v164, v166
	v_min_f32_e32 v169, v164, v166
	v_max_f32_e32 v170, v165, v167
	v_min_f32_e32 v171, v165, v167
	v_max_f32_e32 v172, v170, v169
	v_min_f32_e32 v173, v170, v169
	v_max_f32_e32 v174, v158, v168
	v_min_f32_e32 v38, v158, v168
	v_max_f32_e32 v39, v163, v173
	v_min_f32_e32 v40, v163, v173
	v_max_f32_e32 v41, v39, v38
	v_min_f32_e32 v42, v39, v38
	v_max_f32_e32 v43, v162, v172
	v_min_f32_e32 v44, v162, v172
	v_max_f32_e32 v45, v161, v171
	v_min_f32_e32 v46, v161, v171
	v_max_f32_e32 v47, v45, v44
	v_min_f32_e32 v48, v45, v44
	v_max_f32_e32 v49, v43, v41
	v_min_f32_e32 v50, v43, v41
	v_max_f32_e32 v51, v47, v42
	v_min_f32_e32 v54, v47, v42
	v_max_f32_e32 v55, v48, v40
	v_min_f32_e32 v56, v48, v40
	v_max_f32_e32 v57, v136, v174
	v_min_f32_e32 v58, v136, v174
	v_max_f32_e32 v59, v151, v54
	v_min_f32_e32 v60, v151, v54
	v_max_f32_e32 v61, v59, v58
	v_min_f32_e32 v62, v59, v58
	v_max_f32_e32 v63, v149, v50
	v_min_f32_e32 v6, v149, v50
	v_max_f32_e32 v7, v153, v56
	v_min_f32_e32 v8, v153, v56
	v_max_f32_e32 v9, v7, v6
	v_min_f32_e32 v10, v7, v6
	v_max_f32_e32 v11, v63, v61
	v_min_f32_e32 v12, v63, v61
	v_max_f32_e32 v13, v9, v62
	v_min_f32_e32 v14, v9, v62
	v_max_f32_e32 v15, v10, v60
	v_min_f32_e32 v16, v10, v60
	v_max_f32_e32 v17, v148, v49
	v_min_f32_e32 v18, v148, v49
	v_max_f32_e32 v19, v152, v55
	v_min_f32_e32 v20, v152, v55
	v_max_f32_e32 v21, v19, v18
	v_min_f32_e32 v22, v19, v18
	v_max_f32_e32 v23, v150, v51
	v_min_f32_e32 v24, v150, v51
	v_max_f32_e32 v25, v145, v46
	v_min_f32_e32 v26, v145, v46
	v_max_f32_e32 v27, v25, v24
	v_min_f32_e32 v28, v25, v24
	v_max_f32_e32 v29, v23, v21
	v_min_f32_e32 v30, v23, v21
	v_max_f32_e32 v31, v27, v22
	v_min_f32_e32 v32, v27, v22
	v_max_f32_e32 v33, v28, v20
	v_min_f32_e32 v34, v28, v20
	v_max_f32_e32 v35, v17, v11
	v_min_f32_e32 v36, v17, v11
	v_max_f32_e32 v37, v29, v12
	v_min_f32_e32 v66, v29, v12
	v_max_f32_e32 v67, v30, v13
	v_min_f32_e32 v68, v30, v13
	v_max_f32_e32 v69, v31, v14
	v_min_f32_e32 v116, v31, v14
	v_max_f32_e32 v118, v32, v15
	v_min_f32_e32 v117, v32, v15
	v_max_f32_e32 v119, v33, v16
	v_min_f32_e32 v122, v33, v16
	v_max_f32_e32 v121, v34, v8
	v_min_f32_e32 v70, v34, v8
	v_max_f32_e32 v71, v82, v83
	v_min_f32_e32 v72, v82, v83
	v_max_f32_e32 v73, v84, v85
	v_min_f32_e32 v126, v84, v85
	v_max_f32_e32 v128, v71, v73
	v_min_f32_e32 v127, v71, v73
	v_max_f32_e32 v129, v72, v126
	v_min_f32_e32 v132, v72, v126
	v_max_f32_e32 v131, v129, v127
	v_min_f32_e32 v120, v129, v127
	v_max_f32_e32 v130, v86, v87
	v_min_f32_e32 v125, v86, v87
	v_max_f32_e32 v135, v88, v89
	v_min_f32_e32 v138, v88, v89
	v_max_f32_e32 v137, v130, v135
	v_min_f32_e32 v124, v130, v135
	v_max_f32_e32 v134, v125, v138
	v_min_f32_e32 v123, v125, v138
	v_max_f32_e32 v133, v134, v124
	v_min_f32_e32 v144, v134, v124
	v_max_f32_e32 v143, v128, v137
	v_min_f32_e32 v142, v128, v137
	v_max_f32_e32 v140, v120, v144
	v_min_f32_e32 v146, v120, v144
	v_max_f32_e32 v141, v140, v142
	v_min_f32_e32 v147, v140, v142
	v_max_f32_e32 v139, v131, v133
	v_min_f32_e32 v74, v131, v133
	v_max_f32_e32 v75, v132, v123
	v_min_f32_e32 v76, v132, v123
	v_max_f32_e32 v77, v75, v74
	v_min_f32_e32 v154, v75, v74
	v_max_f32_e32 v156, v139, v141
	v_min_f32_e32 v155, v139, v141
	v_max_f32_e32 v157, v77, v147
	v_min_f32_e32 v160, v77, v147
	v_max_f32_e32 v159, v154, v146
	v_min_f32_e32 v78, v154, v146
	v_max_f32_e32 v79, v90, v91
	v_min_f32_e32 v80, v90, v91
	v_max_f32_e32 v81, v92, v93
	v_min_f32_e32 v164, v92, v93
	v_max_f32_e32 v166, v79, v81
	v_min_f32_e32 v165, v79, v81
	v_max_f32_e32 v167, v80, v164
	v_min_f32_e32 v170, v80, v164
	v_max_f32_e32 v169, v167, v165
	v_min_f32_e32 v158, v167, v165
	v_max_f32_e32 v168, v94, v95
	v_min_f32_e32 v163, v94, v95
	v_max_f32_e32 v173, v96, v97
	v_min_f32_e32 v39, v96, v97
	v_max_f32_e32 v38, v168, v173
	v_min_f32_e32 v162, v168, v173
	v_max_f32_e32 v172, v163, v39
; __device__ __forceinline__ void peer_topk_item(PREF P, int w, char* smem) {
;     ...
; #pragma unroll
;     for (int i = 0; i < 16; ++i)
; #pragma unroll
;       for (int j = 0; j < 16; ++j)
;         if ((i + 1) * (j + 1) <= 16) {
;           float s = a[i] + b[j];
;           s = __uint_as_float((__float_as_uint(s) & ~255u) | (unsigned)(i * 16 + j));
;           ce_insert(top, s);
;         }
	v_min_f32_e32 v161, v163, v39
	v_max_f32_e32 v171, v172, v162
	v_min_f32_e32 v45, v172, v162
	v_max_f32_e32 v44, v166, v38
	v_min_f32_e32 v43, v166, v38
	v_max_f32_e32 v41, v158, v45
	v_min_f32_e32 v47, v158, v45
	v_max_f32_e32 v42, v41, v43
	v_min_f32_e32 v48, v41, v43
	v_max_f32_e32 v40, v169, v171
	v_min_f32_e32 v136, v169, v171
	v_max_f32_e32 v174, v170, v161
	v_min_f32_e32 v151, v170, v161
	v_max_f32_e32 v54, v174, v136
	v_min_f32_e32 v59, v174, v136
	v_max_f32_e32 v58, v40, v42
	v_min_f32_e32 v149, v40, v42
	v_max_f32_e32 v50, v54, v48
	v_min_f32_e32 v153, v54, v48
	v_max_f32_e32 v56, v59, v47
	v_min_f32_e32 v7, v59, v47
	v_max_f32_e32 v6, v143, v44
	v_min_f32_e32 v63, v143, v44
	v_max_f32_e32 v61, v160, v153
	v_min_f32_e32 v9, v160, v153
	v_max_f32_e32 v62, v61, v63
	v_min_f32_e32 v10, v61, v63
	v_max_f32_e32 v60, v155, v149
	v_min_f32_e32 v148, v155, v149
	v_max_f32_e32 v49, v78, v7
	v_min_f32_e32 v152, v78, v7
	v_max_f32_e32 v55, v49, v148
	v_min_f32_e32 v19, v49, v148
	v_max_f32_e32 v18, v60, v62
	v_min_f32_e32 v150, v60, v62
	v_max_f32_e32 v51, v55, v10
	v_min_f32_e32 v145, v55, v10
	v_max_f32_e32 v46, v19, v9
	v_min_f32_e32 v25, v19, v9
	v_max_f32_e32 v24, v156, v58
	v_min_f32_e32 v23, v156, v58
	v_max_f32_e32 v21, v159, v56
	v_min_f32_e32 v27, v159, v56
	v_max_f32_e32 v22, v21, v23
	v_min_f32_e32 v28, v21, v23
	v_max_f32_e32 v20, v157, v50
	v_min_f32_e32 v17, v157, v50
	v_max_f32_e32 v11, v76, v151
	v_min_f32_e32 v29, v76, v151
	v_max_f32_e32 v12, v11, v17
	v_min_f32_e32 v30, v11, v17
	v_max_f32_e32 v13, v20, v22
	v_min_f32_e32 v31, v20, v22
	v_max_f32_e32 v14, v12, v28
	v_min_f32_e32 v32, v12, v28
	v_max_f32_e32 v15, v30, v27
	v_min_f32_e32 v33, v30, v27
	v_max_f32_e32 v16, v24, v18
	v_min_f32_e32 v34, v24, v18
	v_max_f32_e32 v8, v13, v150
	v_min_f32_e32 v82, v13, v150
	v_max_f32_e32 v83, v31, v51
	v_min_f32_e32 v84, v31, v51
	v_max_f32_e32 v85, v14, v145
	v_min_f32_e32 v71, v14, v145
	v_max_f32_e32 v73, v32, v46
	v_min_f32_e32 v72, v32, v46
	v_max_f32_e32 v126, v15, v25
	v_min_f32_e32 v129, v15, v25
	v_max_f32_e32 v127, v33, v152
	v_min_f32_e32 v86, v33, v152
	v_max_f32_e32 v87, v98, v99
	v_min_f32_e32 v88, v98, v99
	v_max_f32_e32 v89, v100, v101
	v_min_f32_e32 v130, v100, v101
	v_max_f32_e32 v135, v87, v89
	v_min_f32_e32 v125, v87, v89
	v_max_f32_e32 v138, v88, v130
	v_min_f32_e32 v134, v88, v130
	v_max_f32_e32 v124, v138, v125
	v_min_f32_e32 v128, v138, v125
	v_max_f32_e32 v137, v102, v103
	v_min_f32_e32 v120, v102, v103
	v_max_f32_e32 v144, v104, v105
	v_min_f32_e32 v140, v104, v105
	v_max_f32_e32 v142, v137, v144
	v_min_f32_e32 v131, v137, v144
	v_max_f32_e32 v133, v120, v140
	v_min_f32_e32 v132, v120, v140
	v_max_f32_e32 v123, v133, v131
	v_min_f32_e32 v75, v133, v131
	v_max_f32_e32 v74, v135, v142
	v_min_f32_e32 v139, v135, v142
	v_max_f32_e32 v141, v128, v75
	v_min_f32_e32 v77, v128, v75
	v_max_f32_e32 v147, v141, v139
	v_min_f32_e32 v154, v141, v139
	v_max_f32_e32 v146, v124, v123
	v_min_f32_e32 v90, v124, v123
	v_max_f32_e32 v91, v134, v132
	v_min_f32_e32 v92, v134, v132
	v_max_f32_e32 v93, v91, v90
	v_min_f32_e32 v79, v91, v90
	v_max_f32_e32 v81, v146, v147
	v_min_f32_e32 v80, v146, v147
	v_max_f32_e32 v164, v93, v154
	v_min_f32_e32 v167, v93, v154
	v_max_f32_e32 v165, v79, v77
	v_min_f32_e32 v94, v79, v77
	v_max_f32_e32 v95, v106, v107
	v_min_f32_e32 v96, v106, v107
	v_max_f32_e32 v97, v108, v109
	v_min_f32_e32 v168, v108, v109
	v_max_f32_e32 v173, v95, v97
	v_min_f32_e32 v163, v95, v97
	v_max_f32_e32 v39, v96, v168
	v_min_f32_e32 v172, v96, v168
	v_max_f32_e32 v162, v39, v163
	v_min_f32_e32 v166, v39, v163
	v_max_f32_e32 v38, v110, v111
	v_min_f32_e32 v158, v110, v111
	v_max_f32_e32 v45, v112, v113
	v_min_f32_e32 v41, v112, v113
	v_max_f32_e32 v43, v38, v45
	v_min_f32_e32 v169, v38, v45
	v_max_f32_e32 v171, v158, v41
	v_min_f32_e32 v170, v158, v41
	v_max_f32_e32 v161, v171, v169
	v_min_f32_e32 v174, v171, v169
	v_max_f32_e32 v136, v173, v43
	v_min_f32_e32 v40, v173, v43
	v_max_f32_e32 v42, v166, v174
	v_min_f32_e32 v54, v166, v174
	v_max_f32_e32 v48, v42, v40
	v_min_f32_e32 v59, v42, v40
	v_max_f32_e32 v47, v162, v161
	v_min_f32_e32 v143, v162, v161
	v_max_f32_e32 v44, v172, v170
	v_min_f32_e32 v160, v172, v170
	v_max_f32_e32 v153, v44, v143
	v_min_f32_e32 v61, v44, v143
	v_max_f32_e32 v63, v47, v48
	v_min_f32_e32 v155, v47, v48
	v_max_f32_e32 v149, v153, v59
	v_min_f32_e32 v78, v153, v59
	v_max_f32_e32 v7, v61, v54
	v_min_f32_e32 v49, v61, v54
	v_max_f32_e32 v148, v74, v136
	v_min_f32_e32 v60, v74, v136
	v_max_f32_e32 v62, v167, v78
	v_min_f32_e32 v55, v167, v78
	v_max_f32_e32 v10, v62, v60
	v_min_f32_e32 v19, v62, v60
	v_max_f32_e32 v9, v80, v155
	v_min_f32_e32 v156, v80, v155
	v_max_f32_e32 v58, v94, v49
	v_min_f32_e32 v159, v94, v49
	v_max_f32_e32 v56, v58, v156
	v_min_f32_e32 v21, v58, v156
	v_max_f32_e32 v23, v9, v10
	v_min_f32_e32 v157, v9, v10
	v_max_f32_e32 v50, v56, v19
	v_min_f32_e32 v76, v56, v19
	v_max_f32_e32 v151, v21, v55
	v_min_f32_e32 v11, v21, v55
	v_max_f32_e32 v17, v81, v63
	v_min_f32_e32 v20, v81, v63
	v_max_f32_e32 v22, v165, v7
	v_min_f32_e32 v12, v165, v7
	v_max_f32_e32 v28, v22, v20
	v_min_f32_e32 v30, v22, v20
	v_max_f32_e32 v27, v164, v149
	v_min_f32_e32 v24, v164, v149
	v_max_f32_e32 v18, v92, v160
	v_min_f32_e32 v13, v92, v160
	v_max_f32_e32 v150, v18, v24
	v_min_f32_e32 v31, v18, v24
	v_max_f32_e32 v51, v27, v28
	v_min_f32_e32 v14, v27, v28
	v_max_f32_e32 v145, v150, v30
	v_min_f32_e32 v32, v150, v30
	v_max_f32_e32 v46, v31, v12
	v_min_f32_e32 v15, v31, v12
	v_max_f32_e32 v25, v17, v23
	v_min_f32_e32 v33, v17, v23
	v_max_f32_e32 v152, v51, v157
	v_min_f32_e32 v98, v51, v157
; __device__ __forceinline__ void peer_topk_item(PREF P, int w, char* smem) {
;     ...
; #pragma unroll
;     for (int i = 0; i < 16; ++i)
; #pragma unroll
;       for (int j = 0; j < 16; ++j)
;         if ((i + 1) * (j + 1) <= 16) {
;           float s = a[i] + b[j];
;           s = __uint_as_float((__float_as_uint(s) & ~255u) | (unsigned)(i * 16 + j));
;           ce_insert(top, s);
;         }
	v_max_f32_e32 v99, v14, v50
	v_min_f32_e32 v100, v14, v50
	v_max_f32_e32 v101, v145, v76
	v_min_f32_e32 v87, v145, v76
	v_max_f32_e32 v89, v32, v151
	v_min_f32_e32 v88, v32, v151
	v_max_f32_e32 v130, v46, v11
	v_min_f32_e32 v138, v46, v11
	v_max_f32_e32 v125, v15, v159
	v_min_f32_e32 v102, v15, v159
	v_max_f32_e32 v103, v114, v115
	v_min_f32_e32 v104, v114, v115
	v_max_f32_e32 v105, v57, v29
	v_max_f32_e32 v137, v35, v86
	v_max_f32_e32 v144, v36, v127
	v_max_f32_e32 v120, v37, v129
	v_max_f32_e32 v140, v66, v126
	v_max_f32_e32 v133, v67, v72
	v_max_f32_e32 v131, v68, v73
	v_max_f32_e32 v135, v69, v71
	v_max_f32_e32 v142, v116, v85
	v_max_f32_e32 v128, v118, v84
	v_max_f32_e32 v75, v117, v83
	v_max_f32_e32 v141, v119, v82
	v_max_f32_e32 v139, v122, v8
	v_max_f32_e32 v124, v121, v34
	v_max_f32_e32 v123, v70, v16
	v_max_f32_e32 v134, v26, v6
	v_max_f32_e32 v132, v105, v142
	v_min_f32_e32 v91, v105, v142
	v_max_f32_e32 v90, v137, v128
	v_min_f32_e32 v146, v137, v128
	v_max_f32_e32 v147, v144, v75
	v_min_f32_e32 v93, v144, v75
	v_max_f32_e32 v154, v120, v141
	v_min_f32_e32 v79, v120, v141
	v_max_f32_e32 v77, v140, v139
	v_min_f32_e32 v106, v140, v139
	v_max_f32_e32 v107, v133, v124
	v_min_f32_e32 v108, v133, v124
	v_max_f32_e32 v109, v131, v123
	v_min_f32_e32 v95, v131, v123
	v_max_f32_e32 v97, v135, v134
	v_min_f32_e32 v96, v135, v134
	v_max_f32_e32 v168, v132, v77
	v_min_f32_e32 v39, v132, v77
	v_max_f32_e32 v163, v90, v107
	v_min_f32_e32 v110, v90, v107
	v_max_f32_e32 v111, v147, v109
	v_min_f32_e32 v112, v147, v109
	v_max_f32_e32 v113, v154, v97
	v_min_f32_e32 v38, v154, v97
	v_max_f32_e32 v45, v91, v106
	v_min_f32_e32 v158, v91, v106
	v_max_f32_e32 v41, v146, v108
	v_min_f32_e32 v171, v146, v108
	v_max_f32_e32 v169, v93, v95
	v_min_f32_e32 v173, v93, v95
	v_max_f32_e32 v43, v79, v96
	v_min_f32_e32 v166, v79, v96
	v_max_f32_e32 v174, v168, v111
	v_min_f32_e32 v42, v168, v111
	v_max_f32_e32 v40, v163, v113
	v_min_f32_e32 v162, v163, v113
	v_max_f32_e32 v161, v39, v112
	v_min_f32_e32 v172, v39, v112
	v_max_f32_e32 v170, v110, v38
	v_min_f32_e32 v44, v110, v38
	v_max_f32_e32 v143, v45, v169
	v_min_f32_e32 v47, v45, v169
	v_max_f32_e32 v48, v41, v43
	v_min_f32_e32 v153, v41, v43
	v_max_f32_e32 v59, v158, v173
	v_min_f32_e32 v61, v158, v173
	v_max_f32_e32 v54, v171, v166
	v_min_f32_e32 v74, v171, v166
	v_max_f32_e32 v136, v174, v40
	v_min_f32_e32 v167, v174, v40
	v_max_f32_e32 v78, v42, v162
	v_min_f32_e32 v62, v42, v162
	v_max_f32_e32 v60, v161, v170
	v_min_f32_e32 v80, v161, v170
	v_max_f32_e32 v155, v172, v44
	v_min_f32_e32 v94, v172, v44
	v_max_f32_e32 v49, v143, v48
	v_min_f32_e32 v58, v143, v48
	v_max_f32_e32 v156, v47, v153
	v_min_f32_e32 v9, v47, v153
	v_max_f32_e32 v10, v59, v54
	v_min_f32_e32 v56, v59, v54
	v_max_f32_e32 v19, v61, v74
	v_min_f32_e32 v21, v61, v74
	v_max_f32_e32 v55, v102, v104
	v_max_f32_e32 v81, v13, v103
	v_max_f32_e32 v63, v148, v87
	v_min_f32_e32 v165, v148, v87
	v_max_f32_e32 v7, v25, v89
	v_min_f32_e32 v22, v25, v89
	v_max_f32_e32 v20, v33, v88
	v_min_f32_e32 v164, v33, v88
	v_max_f32_e32 v149, v152, v130
	v_min_f32_e32 v92, v152, v130
	v_max_f32_e32 v160, v98, v138
	v_min_f32_e32 v18, v98, v138
	v_max_f32_e32 v24, v99, v125
	v_min_f32_e32 v27, v99, v125
	v_max_f32_e32 v28, v100, v55
	v_min_f32_e32 v150, v100, v55
	v_max_f32_e32 v30, v101, v81
	v_min_f32_e32 v31, v101, v81
	v_max_f32_e32 v12, v63, v160
	v_min_f32_e32 v17, v63, v160
	v_max_f32_e32 v23, v7, v24
	v_min_f32_e32 v51, v7, v24
	v_max_f32_e32 v157, v20, v28
	v_min_f32_e32 v14, v20, v28
	v_max_f32_e32 v50, v149, v30
	v_min_f32_e32 v145, v149, v30
	v_max_f32_e32 v76, v165, v18
	v_min_f32_e32 v32, v165, v18
	v_max_f32_e32 v151, v22, v27
	v_min_f32_e32 v46, v22, v27
	v_max_f32_e32 v11, v164, v150
	v_min_f32_e32 v15, v164, v150
	v_max_f32_e32 v159, v92, v31
	v_min_f32_e32 v114, v92, v31
	v_max_f32_e32 v115, v12, v157
	v_min_f32_e32 v57, v12, v157
	v_max_f32_e32 v29, v23, v50
	v_min_f32_e32 v35, v23, v50
	v_max_f32_e32 v86, v17, v14
	v_min_f32_e32 v36, v17, v14
	v_max_f32_e32 v127, v51, v145
	v_min_f32_e32 v37, v51, v145
	v_max_f32_e32 v129, v76, v11
	v_min_f32_e32 v66, v76, v11
	v_max_f32_e32 v126, v151, v159
	v_min_f32_e32 v67, v151, v159
	v_max_f32_e32 v72, v32, v15
	v_min_f32_e32 v68, v32, v15
	v_max_f32_e32 v73, v46, v114
	v_min_f32_e32 v69, v46, v114
	v_max_f32_e32 v71, v115, v29
	v_min_f32_e32 v116, v115, v29
	v_max_f32_e32 v85, v57, v35
	v_min_f32_e32 v118, v57, v35
	v_max_f32_e32 v84, v86, v127
	v_min_f32_e32 v117, v86, v127
	v_max_f32_e32 v83, v36, v37
	v_min_f32_e32 v119, v36, v37
	v_max_f32_e32 v82, v129, v126
	v_min_f32_e32 v122, v129, v126
	v_max_f32_e32 v8, v66, v67
	v_min_f32_e32 v121, v66, v67
	v_max_f32_e32 v34, v72, v73
	v_min_f32_e32 v70, v72, v73
	v_max_f32_e32 v16, v68, v69
	v_min_f32_e32 v26, v68, v69
	v_max_f32_e32 v6, v136, v26
	v_max_f32_e32 v105, v167, v16
	v_max_f32_e32 v142, v78, v70
	v_max_f32_e32 v137, v62, v34
	v_max_f32_e32 v128, v60, v121
	v_max_f32_e32 v144, v80, v8
	v_max_f32_e32 v75, v155, v122
	v_max_f32_e32 v120, v94, v82
	v_max_f32_e32 v141, v49, v119
	v_max_f32_e32 v140, v58, v83
	v_max_f32_e32 v139, v156, v117
	v_max_f32_e32 v133, v9, v84
	v_max_f32_e32 v124, v10, v118
	v_max_f32_e32 v131, v56, v85
	v_max_f32_e32 v123, v19, v116
	v_max_f32_e32 v135, v21, v71
	v_max_f32_e32 v134, v6, v141
	v_min_f32_e32 v132, v6, v141
	v_max_f32_e32 v77, v105, v140
	v_min_f32_e32 v90, v105, v140
	v_max_f32_e32 v107, v142, v139
	v_min_f32_e32 v147, v142, v139
	v_max_f32_e32 v109, v137, v133
	v_min_f32_e32 v154, v137, v133
	v_max_f32_e32 v97, v128, v124
	v_min_f32_e32 v91, v128, v124
	v_max_f32_e32 v106, v144, v131
	v_min_f32_e32 v146, v144, v131
; #define P (*launderP(lp))
; __device__ __forceinline__ void peer_topk_item(PREF P, int w, char* smem) {
;     ...
;         }
;     const float best0 = __uint_as_float(__float_as_uint(top[0]) & ~255u);
;     float ev[16], sum = 0.f;
; #pragma unroll
;     for (int k = 0; k < 16; ++k) {
;       float bk = __uint_as_float(__float_as_uint(top[k]) & ~255u);
;       ev[k] = __expf(bk - best0);
;       sum += ev[k];
;     }
;     const float inv = 1.f / sum;
; #pragma unroll
;     for (int k = 0; k < 16; ++k) {
;       unsigned code = __float_as_uint(top[k]) & 255u;
;       int ia = __float_as_uint(Ll[t * 17 + (code >> 4)]) & 127u;
;       int ib = __float_as_uint(Ll[(64 + t) * 17 + (code & 15u)]) & 127u;
;       P.eidx[(size_t)(t0 + t) * 128 + h * 16 + k] = ia * 128 + ib;
	v_max_f32_e32 v108, v75, v123
	v_min_f32_e32 v93, v75, v123
	v_max_f32_e32 v95, v120, v135
	v_min_f32_e32 v79, v120, v135
	v_max_f32_e32 v96, v134, v97
	v_min_f32_e32 v168, v134, v97
	v_max_f32_e32 v111, v77, v106
	v_min_f32_e32 v163, v77, v106
	v_max_f32_e32 v113, v107, v108
	v_min_f32_e32 v39, v107, v108
	v_max_f32_e32 v112, v109, v95
	v_min_f32_e32 v110, v109, v95
	v_max_f32_e32 v38, v132, v91
	v_min_f32_e32 v45, v132, v91
	v_max_f32_e32 v169, v90, v146
	v_min_f32_e32 v41, v90, v146
	v_max_f32_e32 v43, v147, v93
	v_min_f32_e32 v158, v147, v93
	v_max_f32_e32 v173, v154, v79
	v_min_f32_e32 v171, v154, v79
	v_max_f32_e32 v166, v96, v113
	v_min_f32_e32 v174, v96, v113
	v_max_f32_e32 v40, v111, v112
	v_min_f32_e32 v42, v111, v112
	v_max_f32_e32 v162, v168, v39
	v_min_f32_e32 v161, v168, v39
	v_max_f32_e32 v170, v163, v110
	v_min_f32_e32 v172, v163, v110
	v_max_f32_e32 v44, v38, v43
	v_min_f32_e32 v143, v38, v43
	v_max_f32_e32 v48, v169, v173
	v_min_f32_e32 v47, v169, v173
	v_max_f32_e32 v153, v45, v158
	v_min_f32_e32 v59, v45, v158
	v_max_f32_e32 v54, v41, v171
	v_min_f32_e32 v61, v41, v171
	v_max_f32_e32 v74, v166, v40
	v_min_f32_e32 v102, v166, v40
	v_max_f32_e32 v104, v174, v42
	v_min_f32_e32 v13, v174, v42
	v_max_f32_e32 v103, v162, v170
	v_min_f32_e32 v148, v162, v170
	v_max_f32_e32 v87, v161, v172
	v_min_f32_e32 v25, v161, v172
	v_max_f32_e32 v89, v44, v48
	v_min_f32_e32 v33, v44, v48
	v_max_f32_e32 v88, v143, v47
	v_min_f32_e32 v152, v143, v47
	v_max_f32_e32 v130, v153, v54
	v_min_f32_e32 v98, v153, v54
	v_max_f32_e32 v138, v59, v61
	v_min_f32_e32 v99, v59, v61
	v_add_u32_e32 v40, s16, v53
	v_ashrrev_i32_e32 v41, 31, v40
	v_lshlrev_b64 v[40:41], 9, v[40:41]
	v_lshl_or_b32 v40, s15, 6, v40
	s_waitcnt lgkmcnt(0)
	v_lshl_add_u64 v[2:3], v[2:3], 0, v[40:41]
	v_lshl_add_u64 v[0:1], v[0:1], 0, v[40:41]
	v_bfe_u32 v107, v74, 4, 4
	v_lshl_add_u32 v66, v107, 2, v4
	v_and_b32_e32 v107, 15, v74
	v_lshl_add_u32 v83, v107, 2, v4
	v_bfe_u32 v107, v102, 4, 4
	v_lshl_add_u32 v67, v107, 2, v4
	v_and_b32_e32 v107, 15, v102
	v_lshl_add_u32 v84, v107, 2, v4
	v_bfe_u32 v107, v104, 4, 4
	v_lshl_add_u32 v68, v107, 2, v4
	v_and_b32_e32 v107, 15, v104
	v_lshl_add_u32 v85, v107, 2, v4
	v_bfe_u32 v107, v13, 4, 4
	v_lshl_add_u32 v69, v107, 2, v4
	v_and_b32_e32 v107, 15, v13
	v_lshl_add_u32 v86, v107, 2, v4
	v_bfe_u32 v107, v103, 4, 4
	v_lshl_add_u32 v70, v107, 2, v4
	v_and_b32_e32 v107, 15, v103
	v_lshl_add_u32 v90, v107, 2, v4
	v_bfe_u32 v107, v148, 4, 4
	v_lshl_add_u32 v71, v107, 2, v4
	v_and_b32_e32 v107, 15, v148
	v_lshl_add_u32 v91, v107, 2, v4
	v_bfe_u32 v107, v87, 4, 4
	v_lshl_add_u32 v72, v107, 2, v4
	v_and_b32_e32 v107, 15, v87
	v_lshl_add_u32 v92, v107, 2, v4
	v_bfe_u32 v107, v25, 4, 4
	v_lshl_add_u32 v73, v107, 2, v4
	v_and_b32_e32 v107, 15, v25
	v_lshl_add_u32 v93, v107, 2, v4
	v_bfe_u32 v107, v89, 4, 4
	v_lshl_add_u32 v75, v107, 2, v4
	v_and_b32_e32 v107, 15, v89
	v_lshl_add_u32 v94, v107, 2, v4
	v_bfe_u32 v107, v33, 4, 4
	v_lshl_add_u32 v76, v107, 2, v4
	v_and_b32_e32 v107, 15, v33
	v_lshl_add_u32 v95, v107, 2, v4
	v_bfe_u32 v107, v88, 4, 4
	v_lshl_add_u32 v77, v107, 2, v4
	v_and_b32_e32 v107, 15, v88
	v_lshl_add_u32 v96, v107, 2, v4
	v_bfe_u32 v107, v152, 4, 4
	v_lshl_add_u32 v78, v107, 2, v4
	v_and_b32_e32 v107, 15, v152
	v_lshl_add_u32 v97, v107, 2, v4
	v_bfe_u32 v107, v130, 4, 4
	v_lshl_add_u32 v79, v107, 2, v4
	v_and_b32_e32 v107, 15, v130
	v_lshl_add_u32 v100, v107, 2, v4
	v_bfe_u32 v107, v98, 4, 4
	v_lshl_add_u32 v80, v107, 2, v4
	v_and_b32_e32 v107, 15, v98
	v_lshl_add_u32 v101, v107, 2, v4
	v_bfe_u32 v107, v138, 4, 4
	v_lshl_add_u32 v81, v107, 2, v4
	v_and_b32_e32 v107, 15, v138
	v_lshl_add_u32 v105, v107, 2, v4
	v_bfe_u32 v107, v99, 4, 4
	v_lshl_add_u32 v82, v107, 2, v4
	v_and_b32_e32 v107, 15, v99
	v_lshl_add_u32 v106, v107, 2, v4
	ds_read_b32 v66, v66
	ds_read_b32 v83, v83 offset:4352
	ds_read_b32 v67, v67
	ds_read_b32 v84, v84 offset:4352
	ds_read_b32 v68, v68
	ds_read_b32 v85, v85 offset:4352
	ds_read_b32 v69, v69
	ds_read_b32 v86, v86 offset:4352
	ds_read_b32 v70, v70
	ds_read_b32 v90, v90 offset:4352
	ds_read_b32 v71, v71
	ds_read_b32 v91, v91 offset:4352
	ds_read_b32 v72, v72
	ds_read_b32 v92, v92 offset:4352
	ds_read_b32 v73, v73
	ds_read_b32 v93, v93 offset:4352
	v_and_b32_e32 v108, 0xffffff00, v74
	v_and_b32_e32 v109, 0xffffff00, v74
	v_and_b32_e32 v110, 0xffffff00, v102
	v_and_b32_e32 v111, 0xffffff00, v104
	v_and_b32_e32 v112, 0xffffff00, v13
	v_and_b32_e32 v113, 0xffffff00, v103
	v_and_b32_e32 v114, 0xffffff00, v148
	v_and_b32_e32 v115, 0xffffff00, v87
	v_and_b32_e32 v116, 0xffffff00, v25
	v_and_b32_e32 v117, 0xffffff00, v89
	v_and_b32_e32 v118, 0xffffff00, v33
	v_and_b32_e32 v119, 0xffffff00, v88
	v_and_b32_e32 v120, 0xffffff00, v152
	v_and_b32_e32 v121, 0xffffff00, v130
	v_and_b32_e32 v122, 0xffffff00, v98
	v_and_b32_e32 v123, 0xffffff00, v138
	v_and_b32_e32 v124, 0xffffff00, v99
	v_sub_f32_e32 v109, v109, v108
	v_sub_f32_e32 v110, v110, v108
	v_sub_f32_e32 v111, v111, v108
	v_sub_f32_e32 v112, v112, v108
	v_sub_f32_e32 v113, v113, v108
	v_sub_f32_e32 v114, v114, v108
	v_sub_f32_e32 v115, v115, v108
	v_sub_f32_e32 v116, v116, v108
	v_sub_f32_e32 v117, v117, v108
	v_sub_f32_e32 v118, v118, v108
	v_sub_f32_e32 v119, v119, v108
	v_sub_f32_e32 v120, v120, v108
	v_sub_f32_e32 v121, v121, v108
	v_sub_f32_e32 v122, v122, v108
	v_sub_f32_e32 v123, v123, v108
	v_sub_f32_e32 v124, v124, v108
	v_mul_f32_e32 v109, 0x3fb8aa3b, v109
	v_mul_f32_e32 v110, 0x3fb8aa3b, v110
	v_mul_f32_e32 v111, 0x3fb8aa3b, v111
	v_mul_f32_e32 v112, 0x3fb8aa3b, v112
; #define P (*launderP(lp))
; __device__ __forceinline__ void peer_topk_item(PREF P, int w, char* smem) {
;     ...
;     float ev[16], sum = 0.f;
; #pragma unroll
;     for (int k = 0; k < 16; ++k) {
;       float bk = __uint_as_float(__float_as_uint(top[k]) & ~255u);
;       ev[k] = __expf(bk - best0);
;       sum += ev[k];
;     }
;     const float inv = 1.f / sum;
; #pragma unroll
;     for (int k = 0; k < 16; ++k) {
;       unsigned code = __float_as_uint(top[k]) & 255u;
;       int ia = __float_as_uint(Ll[t * 17 + (code >> 4)]) & 127u;
;       int ib = __float_as_uint(Ll[(64 + t) * 17 + (code & 15u)]) & 127u;
;       P.eidx[(size_t)(t0 + t) * 128 + h * 16 + k] = ia * 128 + ib;
;       P.gw[(size_t)(t0 + t) * 128 + h * 16 + k] = ev[k] * inv;
;     }
	v_mul_f32_e32 v113, 0x3fb8aa3b, v113
	v_mul_f32_e32 v114, 0x3fb8aa3b, v114
	v_mul_f32_e32 v115, 0x3fb8aa3b, v115
	v_mul_f32_e32 v116, 0x3fb8aa3b, v116
	v_mul_f32_e32 v117, 0x3fb8aa3b, v117
	v_mul_f32_e32 v118, 0x3fb8aa3b, v118
	v_mul_f32_e32 v119, 0x3fb8aa3b, v119
	v_mul_f32_e32 v120, 0x3fb8aa3b, v120
	v_mul_f32_e32 v121, 0x3fb8aa3b, v121
	v_mul_f32_e32 v122, 0x3fb8aa3b, v122
	v_mul_f32_e32 v123, 0x3fb8aa3b, v123
	v_mul_f32_e32 v124, 0x3fb8aa3b, v124
	v_exp_f32_e32 v109, v109
	v_exp_f32_e32 v110, v110
	v_exp_f32_e32 v111, v111
	v_exp_f32_e32 v112, v112
	v_exp_f32_e32 v113, v113
	v_exp_f32_e32 v114, v114
	v_exp_f32_e32 v115, v115
	v_exp_f32_e32 v116, v116
	v_exp_f32_e32 v117, v117
	v_exp_f32_e32 v118, v118
	v_exp_f32_e32 v119, v119
	v_exp_f32_e32 v120, v120
	v_exp_f32_e32 v121, v121
	v_exp_f32_e32 v122, v122
	v_exp_f32_e32 v123, v123
	v_exp_f32_e32 v124, v124
	s_nop 0
	v_add_f32_e32 v125, 0, v109
	v_add_f32_e32 v125, v110, v125
	v_add_f32_e32 v125, v111, v125
	v_add_f32_e32 v125, v112, v125
	v_add_f32_e32 v125, v113, v125
	v_add_f32_e32 v125, v114, v125
	v_add_f32_e32 v125, v115, v125
	v_add_f32_e32 v125, v116, v125
	v_add_f32_e32 v125, v117, v125
	v_add_f32_e32 v125, v118, v125
	v_add_f32_e32 v125, v119, v125
	v_add_f32_e32 v125, v120, v125
	v_add_f32_e32 v125, v121, v125
	v_add_f32_e32 v125, v122, v125
	v_add_f32_e32 v125, v123, v125
	v_add_f32_e32 v125, v124, v125
	v_div_scale_f32 v126, s[36:37], v125, v125, 1.0
	v_rcp_f32_e32 v127, v126
	s_nop 0
	v_fma_f32 v128, -v126, v127, 1.0
	v_fmac_f32_e32 v127, v128, v127
	v_div_scale_f32 v129, vcc, 1.0, v125, 1.0
	v_mul_f32_e32 v131, v129, v127
	v_fma_f32 v128, -v126, v131, v129
	v_fmac_f32_e32 v131, v128, v127
	v_fma_f32 v126, -v126, v131, v129
	s_nop 1
	v_div_fmas_f32 v126, v126, v127, v131
	v_div_fixup_f32 v131, v126, v125, 1.0
	v_mul_f32_e32 v109, v109, v131
	v_mul_f32_e32 v110, v110, v131
	v_mul_f32_e32 v111, v111, v131
	v_mul_f32_e32 v112, v112, v131
	v_mul_f32_e32 v113, v113, v131
	v_mul_f32_e32 v114, v114, v131
	v_mul_f32_e32 v115, v115, v131
	v_mul_f32_e32 v116, v116, v131
	v_mul_f32_e32 v117, v117, v131
	v_mul_f32_e32 v118, v118, v131
	v_mul_f32_e32 v119, v119, v131
	v_mul_f32_e32 v120, v120, v131
	v_mul_f32_e32 v121, v121, v131
	v_mul_f32_e32 v122, v122, v131
	v_mul_f32_e32 v123, v123, v131
	v_mul_f32_e32 v124, v124, v131
	ds_read_b32 v75, v75
	ds_read_b32 v94, v94 offset:4352
	ds_read_b32 v76, v76
	ds_read_b32 v95, v95 offset:4352
	ds_read_b32 v77, v77
	ds_read_b32 v96, v96 offset:4352
	ds_read_b32 v78, v78
	ds_read_b32 v97, v97 offset:4352
	ds_read_b32 v79, v79
	ds_read_b32 v100, v100 offset:4352
	ds_read_b32 v80, v80
	ds_read_b32 v101, v101 offset:4352
	ds_read_b32 v81, v81
	ds_read_b32 v105, v105 offset:4352
	ds_read_b32 v82, v82
	ds_read_b32 v106, v106 offset:4352
	v_mov_b32_e32 v140, v109
	v_mov_b32_e32 v141, v110
	v_mov_b32_e32 v142, v111
	v_mov_b32_e32 v143, v112
	v_mov_b32_e32 v144, v113
	v_mov_b32_e32 v145, v114
	v_mov_b32_e32 v146, v115
	v_mov_b32_e32 v147, v116
	v_mov_b32_e32 v148, v117
	v_mov_b32_e32 v149, v118
	v_mov_b32_e32 v150, v119
	v_mov_b32_e32 v151, v120
	v_mov_b32_e32 v152, v121
	v_mov_b32_e32 v153, v122
	v_mov_b32_e32 v154, v123
	v_mov_b32_e32 v155, v124
	flat_store_dwordx4 v[0:1], v[140:143]
	flat_store_dwordx4 v[0:1], v[144:147] offset:16
	flat_store_dwordx4 v[0:1], v[148:151] offset:32
	flat_store_dwordx4 v[0:1], v[152:155] offset:48
	s_waitcnt lgkmcnt(0)
	v_lshlrev_b32_e32 v66, 7, v66
	v_and_b32_e32 v83, 0x7f, v83
	v_and_b32_e32 v66, 0x3f80, v66
	v_or_b32_e32 v156, v66, v83
	v_lshlrev_b32_e32 v67, 7, v67
	v_and_b32_e32 v84, 0x7f, v84
	v_and_b32_e32 v67, 0x3f80, v67
	v_or_b32_e32 v157, v67, v84
	v_lshlrev_b32_e32 v68, 7, v68
	v_and_b32_e32 v85, 0x7f, v85
	v_and_b32_e32 v68, 0x3f80, v68
	v_or_b32_e32 v158, v68, v85
	v_lshlrev_b32_e32 v69, 7, v69
	v_and_b32_e32 v86, 0x7f, v86
	v_and_b32_e32 v69, 0x3f80, v69
	v_or_b32_e32 v159, v69, v86
	v_lshlrev_b32_e32 v70, 7, v70
	v_and_b32_e32 v90, 0x7f, v90
	v_and_b32_e32 v70, 0x3f80, v70
	v_or_b32_e32 v160, v70, v90
	v_lshlrev_b32_e32 v71, 7, v71
	v_and_b32_e32 v91, 0x7f, v91
	v_and_b32_e32 v71, 0x3f80, v71
	v_or_b32_e32 v161, v71, v91
	v_lshlrev_b32_e32 v72, 7, v72
	v_and_b32_e32 v92, 0x7f, v92
	v_and_b32_e32 v72, 0x3f80, v72
	v_or_b32_e32 v162, v72, v92
	v_lshlrev_b32_e32 v73, 7, v73
	v_and_b32_e32 v93, 0x7f, v93
	v_and_b32_e32 v73, 0x3f80, v73
	v_or_b32_e32 v163, v73, v93
	v_lshlrev_b32_e32 v75, 7, v75
	v_and_b32_e32 v94, 0x7f, v94
	v_and_b32_e32 v75, 0x3f80, v75
	v_or_b32_e32 v164, v75, v94
	v_lshlrev_b32_e32 v76, 7, v76
	v_and_b32_e32 v95, 0x7f, v95
	v_and_b32_e32 v76, 0x3f80, v76
	v_or_b32_e32 v165, v76, v95
	v_lshlrev_b32_e32 v77, 7, v77
	v_and_b32_e32 v96, 0x7f, v96
	v_and_b32_e32 v77, 0x3f80, v77
	v_or_b32_e32 v166, v77, v96
	v_lshlrev_b32_e32 v78, 7, v78
	v_and_b32_e32 v97, 0x7f, v97
	v_and_b32_e32 v78, 0x3f80, v78
	v_or_b32_e32 v167, v78, v97
	v_lshlrev_b32_e32 v79, 7, v79
	v_and_b32_e32 v100, 0x7f, v100
	v_and_b32_e32 v79, 0x3f80, v79
	v_or_b32_e32 v168, v79, v100
	v_lshlrev_b32_e32 v80, 7, v80
	v_and_b32_e32 v101, 0x7f, v101
	v_and_b32_e32 v80, 0x3f80, v80
	v_or_b32_e32 v169, v80, v101
	v_lshlrev_b32_e32 v81, 7, v81
	v_and_b32_e32 v105, 0x7f, v105
	v_and_b32_e32 v81, 0x3f80, v81
	v_or_b32_e32 v170, v81, v105
	v_lshlrev_b32_e32 v82, 7, v82
	v_and_b32_e32 v106, 0x7f, v106
	v_and_b32_e32 v82, 0x3f80, v82
	v_or_b32_e32 v171, v82, v106
	flat_store_dwordx4 v[2:3], v[156:159]
	flat_store_dwordx4 v[2:3], v[160:163] offset:16
	flat_store_dwordx4 v[2:3], v[164:167] offset:32
	flat_store_dwordx4 v[2:3], v[168:171] offset:48
	s_branch .LBB0_626
